# ln2 of the sample rows fused into the phase-11 sample tail via a 16-workgroup statistics rendezvous; last grid barrier and phase 12 removed
# baseline (speedup 1.0000x reference)
.LBB0_1340:
	v_or_b32_e32 v0, s20, v55
	v_mad_i64_i32 v[48:49], s[20:21], v0, s14, v[34:35]
	v_or_b32_e32 v0, s19, v55
	v_mul_u32_u24_e32 v4, 0xb00, v0
	global_load_dwordx4 v[0:3], v[48:49], off
	v_lshlrev_b32_e32 v4, 1, v4
	v_mov_b32_e32 v5, v33
	v_lshl_add_u64 v[104:105], v[36:37], 0, v[4:5]
	global_load_dwordx4 v[4:7], v[104:105], off
	v_add_co_u32_e32 v106, vcc, s15, v104
	v_ashrrev_i32_e32 v45, 31, v44
	s_nop 0
	v_addc_co_u32_e32 v107, vcc, 0, v105, vcc
	global_load_dwordx4 v[8:11], v[106:107], off
	global_load_dwordx4 v[72:75], v[48:49], off offset:32
	global_load_dwordx4 v[76:79], v[104:105], off offset:32
	global_load_dwordx4 v[80:83], v[48:49], off offset:672
	global_load_dwordx4 v[84:87], v[106:107], off offset:32
	global_load_dwordx4 v[88:91], v[48:49], off offset:64
	global_load_dwordx4 v[92:95], v[104:105], off offset:672
	global_load_dwordx4 v[96:99], v[104:105], off offset:64
	s_add_i32 s18, s18, s92
	s_add_i32 s8, s8, s9
	s_add_i32 s10, s10, s11
	s_cmpk_lt_i32 s18, 0x100
	s_waitcnt vmcnt(8)
	v_mfma_f32_32x32x16_bf16 v[16:31], v[0:3], v[4:7], 0
	s_waitcnt vmcnt(7)
	v_mfma_f32_32x32x16_bf16 v[0:15], v[0:3], v[8:11], 0
	s_waitcnt vmcnt(5)
	v_mfma_f32_32x32x16_bf16 v[16:31], v[72:75], v[76:79], v[16:31]
	global_load_dwordx4 v[76:79], v[106:107], off offset:64
	global_load_dwordx4 v[100:103], v[48:49], off offset:96
	s_waitcnt vmcnt(5)
	v_mfma_f32_32x32x16_bf16 v[0:15], v[72:75], v[84:87], v[0:15]
	global_load_dwordx4 v[72:75], v[104:105], off offset:96
	s_waitcnt vmcnt(3)
	v_mfma_f32_32x32x16_bf16 v[16:31], v[88:91], v[96:99], v[16:31]
	global_load_dwordx4 v[84:87], v[106:107], off offset:96
	global_load_dwordx4 v[96:99], v[48:49], off offset:128
	s_waitcnt vmcnt(4)
	v_mfma_f32_32x32x16_bf16 v[0:15], v[88:91], v[76:79], v[0:15]
	global_load_dwordx4 v[76:79], v[104:105], off offset:128
	s_waitcnt vmcnt(3)
	v_mfma_f32_32x32x16_bf16 v[16:31], v[100:103], v[72:75], v[16:31]
	global_load_dwordx4 v[72:75], v[106:107], off offset:128
	global_load_dwordx4 v[88:91], v[48:49], off offset:160
	s_waitcnt vmcnt(4)
	v_mfma_f32_32x32x16_bf16 v[0:15], v[100:103], v[84:87], v[0:15]
	global_load_dwordx4 v[84:87], v[104:105], off offset:160
	s_waitcnt vmcnt(3)
	v_mfma_f32_32x32x16_bf16 v[16:31], v[96:99], v[76:79], v[16:31]
	global_load_dwordx4 v[76:79], v[106:107], off offset:160
	global_load_dwordx4 v[100:103], v[48:49], off offset:192
	s_waitcnt vmcnt(4)
	v_mfma_f32_32x32x16_bf16 v[0:15], v[96:99], v[72:75], v[0:15]
	global_load_dwordx4 v[72:75], v[104:105], off offset:192
	s_waitcnt vmcnt(3)
	v_mfma_f32_32x32x16_bf16 v[16:31], v[88:91], v[84:87], v[16:31]
	global_load_dwordx4 v[84:87], v[106:107], off offset:192
	global_load_dwordx4 v[96:99], v[48:49], off offset:224
	s_waitcnt vmcnt(4)
	v_mfma_f32_32x32x16_bf16 v[0:15], v[88:91], v[76:79], v[0:15]
	global_load_dwordx4 v[76:79], v[104:105], off offset:224
	s_waitcnt vmcnt(3)
	v_mfma_f32_32x32x16_bf16 v[16:31], v[100:103], v[72:75], v[16:31]
	global_load_dwordx4 v[72:75], v[106:107], off offset:224
	global_load_dwordx4 v[88:91], v[48:49], off offset:256
	s_waitcnt vmcnt(4)
	v_mfma_f32_32x32x16_bf16 v[0:15], v[100:103], v[84:87], v[0:15]
	global_load_dwordx4 v[84:87], v[104:105], off offset:256
	s_waitcnt vmcnt(3)
	v_mfma_f32_32x32x16_bf16 v[16:31], v[96:99], v[76:79], v[16:31]
	global_load_dwordx4 v[76:79], v[106:107], off offset:256
	global_load_dwordx4 v[100:103], v[48:49], off offset:288
	s_waitcnt vmcnt(4)
	v_mfma_f32_32x32x16_bf16 v[0:15], v[96:99], v[72:75], v[0:15]
	global_load_dwordx4 v[72:75], v[104:105], off offset:288
	s_waitcnt vmcnt(3)
	v_mfma_f32_32x32x16_bf16 v[16:31], v[88:91], v[84:87], v[16:31]
	global_load_dwordx4 v[84:87], v[106:107], off offset:288
	global_load_dwordx4 v[96:99], v[48:49], off offset:320
	s_waitcnt vmcnt(4)
	v_mfma_f32_32x32x16_bf16 v[0:15], v[88:91], v[76:79], v[0:15]
	global_load_dwordx4 v[76:79], v[104:105], off offset:320
	s_waitcnt vmcnt(3)
	v_mfma_f32_32x32x16_bf16 v[16:31], v[100:103], v[72:75], v[16:31]
	global_load_dwordx4 v[72:75], v[106:107], off offset:320
	global_load_dwordx4 v[88:91], v[48:49], off offset:352
	s_waitcnt vmcnt(4)
	v_mfma_f32_32x32x16_bf16 v[0:15], v[100:103], v[84:87], v[0:15]
	global_load_dwordx4 v[84:87], v[104:105], off offset:352
	s_waitcnt vmcnt(3)
	v_mfma_f32_32x32x16_bf16 v[16:31], v[96:99], v[76:79], v[16:31]
	global_load_dwordx4 v[76:79], v[106:107], off offset:352
	global_load_dwordx4 v[100:103], v[48:49], off offset:384
	s_waitcnt vmcnt(4)
	v_mfma_f32_32x32x16_bf16 v[0:15], v[96:99], v[72:75], v[0:15]
	global_load_dwordx4 v[72:75], v[104:105], off offset:384
	s_waitcnt vmcnt(3)
	v_mfma_f32_32x32x16_bf16 v[16:31], v[88:91], v[84:87], v[16:31]
	global_load_dwordx4 v[84:87], v[106:107], off offset:384
	global_load_dwordx4 v[96:99], v[48:49], off offset:416
	s_waitcnt vmcnt(4)
	v_mfma_f32_32x32x16_bf16 v[0:15], v[88:91], v[76:79], v[0:15]
	global_load_dwordx4 v[76:79], v[104:105], off offset:416
	s_waitcnt vmcnt(3)
	v_mfma_f32_32x32x16_bf16 v[16:31], v[100:103], v[72:75], v[16:31]
	global_load_dwordx4 v[72:75], v[106:107], off offset:416
	global_load_dwordx4 v[88:91], v[48:49], off offset:448
	s_waitcnt vmcnt(4)
	v_mfma_f32_32x32x16_bf16 v[0:15], v[100:103], v[84:87], v[0:15]
	global_load_dwordx4 v[84:87], v[104:105], off offset:448
	s_waitcnt vmcnt(3)
	v_mfma_f32_32x32x16_bf16 v[16:31], v[96:99], v[76:79], v[16:31]
	global_load_dwordx4 v[76:79], v[106:107], off offset:448
	global_load_dwordx4 v[100:103], v[48:49], off offset:480
	s_waitcnt vmcnt(4)
	v_mfma_f32_32x32x16_bf16 v[0:15], v[96:99], v[72:75], v[0:15]
	global_load_dwordx4 v[72:75], v[104:105], off offset:480
	s_waitcnt vmcnt(3)
	v_mfma_f32_32x32x16_bf16 v[16:31], v[88:91], v[84:87], v[16:31]
	global_load_dwordx4 v[84:87], v[106:107], off offset:480
	global_load_dwordx4 v[96:99], v[48:49], off offset:512
	s_waitcnt vmcnt(4)
	v_mfma_f32_32x32x16_bf16 v[0:15], v[88:91], v[76:79], v[0:15]
	global_load_dwordx4 v[76:79], v[104:105], off offset:512
	s_waitcnt vmcnt(3)
	v_mfma_f32_32x32x16_bf16 v[16:31], v[100:103], v[72:75], v[16:31]
	global_load_dwordx4 v[72:75], v[106:107], off offset:512
	global_load_dwordx4 v[88:91], v[48:49], off offset:544
	s_waitcnt vmcnt(4)
	v_mfma_f32_32x32x16_bf16 v[0:15], v[100:103], v[84:87], v[0:15]
	global_load_dwordx4 v[84:87], v[104:105], off offset:544
	s_waitcnt vmcnt(3)
	v_mfma_f32_32x32x16_bf16 v[16:31], v[96:99], v[76:79], v[16:31]
	global_load_dwordx4 v[76:79], v[106:107], off offset:544
	global_load_dwordx4 v[100:103], v[48:49], off offset:576
	s_waitcnt vmcnt(4)
	v_mfma_f32_32x32x16_bf16 v[0:15], v[96:99], v[72:75], v[0:15]
	global_load_dwordx4 v[72:75], v[104:105], off offset:576
	s_waitcnt vmcnt(3)
	v_mfma_f32_32x32x16_bf16 v[16:31], v[88:91], v[84:87], v[16:31]
	global_load_dwordx4 v[84:87], v[106:107], off offset:576
	s_waitcnt vmcnt(3)
	v_mfma_f32_32x32x16_bf16 v[0:15], v[88:91], v[76:79], v[0:15]
	s_waitcnt vmcnt(1)
	v_mfma_f32_32x32x16_bf16 v[16:31], v[100:103], v[72:75], v[16:31]
	global_load_dwordx4 v[72:75], v[48:49], off offset:608
	s_waitcnt vmcnt(1)
	v_mfma_f32_32x32x16_bf16 v[0:15], v[100:103], v[84:87], v[0:15]
	global_load_dwordx4 v[76:79], v[104:105], off offset:608
	global_load_dwordx4 v[84:87], v[48:49], off offset:640
	global_load_dwordx4 v[88:91], v[104:105], off offset:640
	v_lshlrev_b64 v[48:49], 11, v[44:45]
	v_lshl_add_u64 v[46:47], v[46:47], 0, v[48:49]
	s_waitcnt vmcnt(2)
	v_mfma_f32_32x32x16_bf16 v[16:31], v[72:75], v[76:79], v[16:31]
	global_load_dwordx4 v[76:79], v[106:107], off offset:608
	global_load_dwordx4 v[96:99], v[106:107], off offset:640
	s_nop 0
	global_load_ushort v46, v[46:47], off
	v_lshlrev_b32_e32 v47, 16, v71
	s_waitcnt vmcnt(2)
	v_mfma_f32_32x32x16_bf16 v[0:15], v[72:75], v[76:79], v[0:15]
	global_load_dwordx4 v[72:75], v[106:107], off offset:672
	v_mfma_f32_32x32x16_bf16 v[16:31], v[84:87], v[88:91], v[16:31]
	s_waitcnt vmcnt(2)
	v_mfma_f32_32x32x16_bf16 v[0:15], v[84:87], v[96:99], v[0:15]
	v_mfma_f32_32x32x16_bf16 v[16:31], v[80:83], v[92:95], v[16:31]
	s_waitcnt vmcnt(0)
	v_mfma_f32_32x32x16_bf16 v[0:15], v[80:83], v[72:75], v[0:15]
	s_nop 9
	ds_write2st64_b32 v56, v16, v17 offset1:1
	ds_write2st64_b32 v56, v18, v19 offset0:2 offset1:3
	ds_write2st64_b32 v56, v20, v21 offset0:4 offset1:5
	ds_write2st64_b32 v56, v22, v23 offset0:6 offset1:7
	ds_write2st64_b32 v56, v24, v25 offset0:8 offset1:9
	ds_write2st64_b32 v56, v26, v27 offset0:10 offset1:11
	ds_write2st64_b32 v56, v28, v29 offset0:12 offset1:13
	ds_write2st64_b32 v56, v30, v31 offset0:14 offset1:15
	ds_write2st64_b32 v56, v0, v1 offset0:16 offset1:17
	ds_write2st64_b32 v56, v2, v3 offset0:18 offset1:19
	ds_write2st64_b32 v56, v4, v5 offset0:20 offset1:21
	ds_write2st64_b32 v56, v6, v7 offset0:22 offset1:23
	ds_write2st64_b32 v56, v8, v9 offset0:24 offset1:25
	ds_write2st64_b32 v56, v10, v11 offset0:26 offset1:27
	ds_write2st64_b32 v56, v12, v13 offset0:28 offset1:29
	ds_write2st64_b32 v56, v14, v15 offset0:30 offset1:31
	s_waitcnt lgkmcnt(0)
	s_barrier
	ds_read2st64_b32 v[0:1], v57 offset1:32
	ds_read2st64_b32 v[2:3], v57 offset0:64 offset1:96
	ds_read2st64_b32 v[4:5], v57 offset0:128 offset1:160
	v_lshlrev_b32_e32 v7, 16, v69
	v_lshlrev_b32_e32 v6, 16, v70
	s_waitcnt lgkmcnt(2)
	v_add_f32_e32 v0, 0, v0
	v_add_f32_e32 v0, v0, v1
	s_waitcnt lgkmcnt(1)
	v_add_f32_e32 v2, v0, v2
	ds_read2st64_b32 v[0:1], v57 offset0:192 offset1:224
	v_add_f32_e32 v2, v2, v3
	s_waitcnt lgkmcnt(1)
	v_add_f32_e32 v4, v2, v4
	ds_read2st64_b32 v[2:3], v58 offset1:32
	v_add_f32_e32 v4, v4, v5
	s_waitcnt lgkmcnt(1)
	v_add_f32_e32 v0, v4, v0
	ds_read2st64_b32 v[4:5], v58 offset0:64 offset1:96
	v_add_f32_e32 v9, v0, v1
	s_waitcnt lgkmcnt(1)
	v_add_f32_e32 v2, 0, v2
	ds_read2st64_b32 v[0:1], v58 offset0:128 offset1:160
	v_add_f32_e32 v2, v2, v3
	s_waitcnt lgkmcnt(1)
	v_add_f32_e32 v4, v2, v4
	ds_read2st64_b32 v[2:3], v58 offset0:192 offset1:224
	v_add_f32_e32 v4, v4, v5
	s_waitcnt lgkmcnt(1)
	v_add_f32_e32 v0, v4, v0
	ds_read2st64_b32 v[4:5], v59 offset1:32
	v_add_f32_e32 v0, v0, v1
	s_waitcnt lgkmcnt(1)
	v_add_f32_e32 v2, v0, v2
	ds_read2st64_b32 v[0:1], v59 offset0:64 offset1:96
	v_add_f32_e32 v10, v2, v3
	s_waitcnt lgkmcnt(1)
	v_add_f32_e32 v4, 0, v4
	ds_read2st64_b32 v[2:3], v59 offset0:128 offset1:160
	v_add_f32_e32 v4, v4, v5
	s_waitcnt lgkmcnt(1)
	v_add_f32_e32 v0, v4, v0
	ds_read2st64_b32 v[4:5], v59 offset0:192 offset1:224
	v_add_f32_e32 v0, v0, v1
	s_waitcnt lgkmcnt(1)
	v_add_f32_e32 v2, v0, v2
	ds_read2st64_b32 v[0:1], v60 offset1:32
	v_add_f32_e32 v2, v2, v3
	s_waitcnt lgkmcnt(1)
	v_add_f32_e32 v2, v2, v4
	v_add_f32_e32 v11, v2, v5
	ds_read2st64_b32 v[2:3], v60 offset0:64 offset1:96
	ds_read2st64_b32 v[4:5], v60 offset0:128 offset1:160
	s_waitcnt lgkmcnt(2)
	v_add_f32_e32 v0, 0, v0
	v_add_f32_e32 v12, v0, v1
	ds_read2st64_b32 v[0:1], v60 offset0:192 offset1:224
	s_waitcnt lgkmcnt(2)
	v_add_f32_e32 v2, v12, v2
	v_add_f32_e32 v2, v2, v3
	s_waitcnt lgkmcnt(1)
	v_add_f32_e32 v2, v2, v4
	v_add_f32_e32 v2, v2, v5
	s_waitcnt lgkmcnt(0)
	v_add_f32_e32 v0, v2, v0
	v_add_f32_e32 v2, v0, v1
	s_load_dwordx2 s[40:41], s[0:1], 0xf0
	s_load_dwordx4 s[44:47], s[0:1], 0xd8
	v_add_f32_e32 v12, v62, v9
	v_mul_f32_e32 v12, v61, v12
	v_fmac_f32_e32 v12, 0x3f9837f0, v7
	s_barrier
	v_lshlrev_b32_e32 v8, 16, v46
	v_add_f32_e32 v13, v65, v10
	v_mul_f32_e32 v13, v64, v13
	v_fmac_f32_e32 v13, 0x3f9837f0, v6
	v_add_f32_e32 v14, v63, v11
	v_mul_f32_e32 v14, v66, v14
	v_fmac_f32_e32 v14, 0x3f9837f0, v47
	v_add_f32_e32 v15, v68, v2
	v_mul_f32_e32 v15, v67, v15
	v_fmac_f32_e32 v15, 0x3f9837f0, v8
	s_lshr_b32 s48, s96, 4
	s_and_b32 s49, s96, 15
	s_lshl_b32 s51, s49, 3
	s_waitcnt lgkmcnt(0)
	global_load_dword v16, v32, s[44:45]
	global_load_dword v17, v32, s[46:47]
	s_lshl_b32 s50, s48, 12
	s_add_u32 s42, s40, 0xff00000
	s_addc_u32 s43, s41, 0
	s_add_u32 s42, s42, s50
	s_addc_u32 s43, s43, 0
	s_lshl_b32 s50, s48, 8
	s_add_u32 s40, s40, 0x27a4080
	s_addc_u32 s41, s41, 0
	s_add_u32 s40, s40, s50
	s_addc_u32 s41, s41, 0
	v_mov_b32_e32 v24, v12
	v_mov_b32_e32 v26, v13
	v_mov_b32_e32 v28, v14
	v_mov_b32_e32 v30, v15
	s_nop 1
	v_add_f32_dpp v24, v24, v24 quad_perm:[1,0,3,2] row_mask:0xf bank_mask:0xf
	v_add_f32_dpp v26, v26, v26 quad_perm:[1,0,3,2] row_mask:0xf bank_mask:0xf
	v_add_f32_dpp v28, v28, v28 quad_perm:[1,0,3,2] row_mask:0xf bank_mask:0xf
	v_add_f32_dpp v30, v30, v30 quad_perm:[1,0,3,2] row_mask:0xf bank_mask:0xf
	v_add_f32_dpp v24, v24, v24 quad_perm:[2,3,0,1] row_mask:0xf bank_mask:0xf
	v_add_f32_dpp v26, v26, v26 quad_perm:[2,3,0,1] row_mask:0xf bank_mask:0xf
	v_add_f32_dpp v28, v28, v28 quad_perm:[2,3,0,1] row_mask:0xf bank_mask:0xf
	v_add_f32_dpp v30, v30, v30 quad_perm:[2,3,0,1] row_mask:0xf bank_mask:0xf
	v_add_f32_dpp v24, v24, v24 row_half_mirror row_mask:0xf bank_mask:0xf
	v_add_f32_dpp v26, v26, v26 row_half_mirror row_mask:0xf bank_mask:0xf
	v_add_f32_dpp v28, v28, v28 row_half_mirror row_mask:0xf bank_mask:0xf
	v_add_f32_dpp v30, v30, v30 row_half_mirror row_mask:0xf bank_mask:0xf
	v_add_f32_dpp v24, v24, v24 row_mirror row_mask:0xf bank_mask:0xf
	v_add_f32_dpp v26, v26, v26 row_mirror row_mask:0xf bank_mask:0xf
	v_add_f32_dpp v28, v28, v28 row_mirror row_mask:0xf bank_mask:0xf
	v_add_f32_dpp v30, v30, v30 row_mirror row_mask:0xf bank_mask:0xf
	s_nop 1
	v_readlane_b32 s52, v24, 0
	v_readlane_b32 s53, v24, 16
	v_readlane_b32 s54, v24, 32
	v_readlane_b32 s55, v24, 48
	v_readlane_b32 s56, v26, 0
	v_readlane_b32 s57, v26, 16
	v_readlane_b32 s58, v26, 32
	v_readlane_b32 s59, v26, 48
	v_readlane_b32 s60, v28, 0
	v_readlane_b32 s61, v28, 16
	v_readlane_b32 s62, v28, 32
	v_readlane_b32 s63, v28, 48
	v_readlane_b32 s64, v30, 0
	v_readlane_b32 s65, v30, 16
	v_readlane_b32 s66, v30, 32
	v_readlane_b32 s67, v30, 48
	v_mov_b32_e32 v24, s52
	v_add_f32_e32 v24, s53, v24
	v_add_f32_e32 v24, s54, v24
	v_add_f32_e32 v24, s55, v24
	v_mov_b32_e32 v26, s56
	v_add_f32_e32 v26, s57, v26
	v_add_f32_e32 v26, s58, v26
	v_add_f32_e32 v26, s59, v26
	v_mov_b32_e32 v28, s60
	v_add_f32_e32 v28, s61, v28
	v_add_f32_e32 v28, s62, v28
	v_add_f32_e32 v28, s63, v28
	v_mov_b32_e32 v30, s64
	v_add_f32_e32 v30, s65, v30
	v_add_f32_e32 v30, s66, v30
	v_add_f32_e32 v30, s67, v30
	v_mul_f32_e32 v24, 0x3c800000, v24
	v_mul_f32_e32 v26, 0x3c800000, v26
	v_mul_f32_e32 v28, 0x3c800000, v28
	v_mul_f32_e32 v30, 0x3c800000, v30
	v_sub_f32_e32 v25, v12, v24
	v_sub_f32_e32 v27, v13, v26
	v_sub_f32_e32 v29, v14, v28
	v_sub_f32_e32 v31, v15, v30
	v_mul_f32_e32 v25, v25, v25
	v_mul_f32_e32 v27, v27, v27
	v_mul_f32_e32 v29, v29, v29
	v_mul_f32_e32 v31, v31, v31
	s_nop 1
	v_add_f32_dpp v25, v25, v25 quad_perm:[1,0,3,2] row_mask:0xf bank_mask:0xf
	v_add_f32_dpp v27, v27, v27 quad_perm:[1,0,3,2] row_mask:0xf bank_mask:0xf
	v_add_f32_dpp v29, v29, v29 quad_perm:[1,0,3,2] row_mask:0xf bank_mask:0xf
	v_add_f32_dpp v31, v31, v31 quad_perm:[1,0,3,2] row_mask:0xf bank_mask:0xf
	v_add_f32_dpp v25, v25, v25 quad_perm:[2,3,0,1] row_mask:0xf bank_mask:0xf
	v_add_f32_dpp v27, v27, v27 quad_perm:[2,3,0,1] row_mask:0xf bank_mask:0xf
	v_add_f32_dpp v29, v29, v29 quad_perm:[2,3,0,1] row_mask:0xf bank_mask:0xf
	v_add_f32_dpp v31, v31, v31 quad_perm:[2,3,0,1] row_mask:0xf bank_mask:0xf
	v_add_f32_dpp v25, v25, v25 row_half_mirror row_mask:0xf bank_mask:0xf
	v_add_f32_dpp v27, v27, v27 row_half_mirror row_mask:0xf bank_mask:0xf
	v_add_f32_dpp v29, v29, v29 row_half_mirror row_mask:0xf bank_mask:0xf
	v_add_f32_dpp v31, v31, v31 row_half_mirror row_mask:0xf bank_mask:0xf
	v_add_f32_dpp v25, v25, v25 row_mirror row_mask:0xf bank_mask:0xf
	v_add_f32_dpp v27, v27, v27 row_mirror row_mask:0xf bank_mask:0xf
	v_add_f32_dpp v29, v29, v29 row_mirror row_mask:0xf bank_mask:0xf
	v_add_f32_dpp v31, v31, v31 row_mirror row_mask:0xf bank_mask:0xf
	s_nop 1
	v_readlane_b32 s52, v25, 0
	v_readlane_b32 s53, v25, 16
	v_readlane_b32 s54, v25, 32
	v_readlane_b32 s55, v25, 48
	v_readlane_b32 s56, v27, 0
	v_readlane_b32 s57, v27, 16
	v_readlane_b32 s58, v27, 32
	v_readlane_b32 s59, v27, 48
	v_readlane_b32 s60, v29, 0
	v_readlane_b32 s61, v29, 16
	v_readlane_b32 s62, v29, 32
	v_readlane_b32 s63, v29, 48
	v_readlane_b32 s64, v31, 0
	v_readlane_b32 s65, v31, 16
	v_readlane_b32 s66, v31, 32
	v_readlane_b32 s67, v31, 48
	v_mov_b32_e32 v25, s52
	v_add_f32_e32 v25, s53, v25
	v_add_f32_e32 v25, s54, v25
	v_add_f32_e32 v25, s55, v25
	v_mov_b32_e32 v27, s56
	v_add_f32_e32 v27, s57, v27
	v_add_f32_e32 v27, s58, v27
	v_add_f32_e32 v27, s59, v27
	v_mov_b32_e32 v29, s60
	v_add_f32_e32 v29, s61, v29
	v_add_f32_e32 v29, s62, v29
	v_add_f32_e32 v29, s63, v29
	v_mov_b32_e32 v31, s64
	v_add_f32_e32 v31, s65, v31
	v_add_f32_e32 v31, s66, v31
	v_add_f32_e32 v31, s67, v31
	v_lshlrev_b32_e32 v20, 7, v51
	v_add_u32_e32 v20, s51, v20
	v_mov_b32_e32 v21, 0
	v_mov_b32_e32 v22, 1
	s_mov_b64 exec, 1
	global_store_dwordx2 v20, v[24:25], s[42:43] sc1
	global_store_dwordx2 v20, v[26:27], s[42:43] offset:1024 sc1
	global_store_dwordx2 v20, v[28:29], s[42:43] offset:2048 sc1
	global_store_dwordx2 v20, v[30:31], s[42:43] offset:3072 sc1
	s_waitcnt vmcnt(0)
	global_atomic_add v21, v22, s[40:41]
	s_mov_b64 exec, -1
	v_lshrrev_b32_e32 v20, 4, v50
	v_lshlrev_b32_e32 v20, 10, v20
	v_and_b32_e32 v23, 15, v50
	v_lshl_add_u32 v20, v23, 3, v20
	v_lshl_add_u32 v20, v51, 7, v20
	s_movk_i32 s56, 0x2000
.Lp12_spin:
	global_load_dword v23, v21, s[40:41] sc1
	s_waitcnt vmcnt(0)
	v_readfirstlane_b32 s57, v23
	s_nop 1
	s_cmp_ge_u32 s57, 0x80
	s_cbranch_scc1 .Lp12_go
	s_sleep 2
	s_sub_u32 s56, s56, 1
	s_cmp_lg_u32 s56, 0
	s_cbranch_scc1 .Lp12_spin
.Lp12_go:
	buffer_inv sc1
	global_load_dwordx2 v[24:25], v20, s[42:43] sc1
	s_waitcnt vmcnt(0)
	v_mov_b32_e32 v26, v24
	s_nop 1
	v_add_f32_dpp v26, v26, v26 quad_perm:[1,0,3,2] row_mask:0xf bank_mask:0xf
	s_nop 1
	v_add_f32_dpp v26, v26, v26 quad_perm:[2,3,0,1] row_mask:0xf bank_mask:0xf
	s_nop 1
	v_add_f32_dpp v26, v26, v26 row_half_mirror row_mask:0xf bank_mask:0xf
	s_nop 1
	v_add_f32_dpp v26, v26, v26 row_mirror row_mask:0xf bank_mask:0xf
	v_mul_f32_e32 v26, 0x3d800000, v26
	v_sub_f32_e32 v27, v24, v26
	v_mul_f32_e32 v27, v27, v27
	v_fmac_f32_e32 v25, 0x42800000, v27
	s_nop 1
	v_add_f32_dpp v25, v25, v25 quad_perm:[1,0,3,2] row_mask:0xf bank_mask:0xf
	s_nop 1
	v_add_f32_dpp v25, v25, v25 quad_perm:[2,3,0,1] row_mask:0xf bank_mask:0xf
	s_nop 1
	v_add_f32_dpp v25, v25, v25 row_half_mirror row_mask:0xf bank_mask:0xf
	s_nop 1
	v_add_f32_dpp v25, v25, v25 row_mirror row_mask:0xf bank_mask:0xf
	v_mov_b32_e32 v28, 0x3727c5ac
	v_fmac_f32_e32 v28, 0x3a800000, v25
	v_rsq_f32_e32 v28, v28
	s_nop 1
	v_readlane_b32 s60, v26, 0
	v_readlane_b32 s61, v28, 0
	v_readlane_b32 s62, v26, 16
	v_readlane_b32 s63, v28, 16
	v_readlane_b32 s64, v26, 32
	v_readlane_b32 s65, v28, 32
	v_readlane_b32 s66, v26, 48
	v_readlane_b32 s67, v28, 48
	v_subrev_f32_e32 v12, s60, v12
	v_subrev_f32_e32 v13, s62, v13
	v_subrev_f32_e32 v14, s64, v14
	v_subrev_f32_e32 v15, s66, v15
	v_mul_f32_e32 v12, s61, v12
	v_mul_f32_e32 v13, s63, v13
	v_mul_f32_e32 v14, s65, v14
	v_mul_f32_e32 v15, s67, v15
	v_fma_f32 v12, v12, v16, v17
	v_fma_f32 v13, v13, v16, v17
	v_fma_f32 v14, v14, v16, v17
	v_fma_f32 v15, v15, v16, v17
	v_lshl_add_u32 v18, v38, 12, v32
	global_store_dword v18, v12, s[22:23]
	v_lshl_add_u32 v19, v40, 12, v32
	global_store_dword v19, v13, s[22:23]
	v_lshl_add_u32 v18, v42, 12, v32
	global_store_dword v18, v14, s[22:23]
	v_lshl_add_u32 v19, v44, 12, v32
	global_store_dword v19, v15, s[22:23]
	s_branch .LBB0_1349

.LBB0_1349:
.LBB0_1404:
	v_readlane_b32 s2, v248, 1
	s_nop 1
	v_add_u32_e32 v0, s2, v192
	s_movk_i32 s2, 0x5800
	v_cmp_gt_i32_e32 vcc, s2, v0
	s_and_saveexec_b64 s[2:3], vcc
	s_cbranch_execz .LBB0_1407
	s_load_dwordx4 s[4:7], s[0:1], 0xe8
	s_lshl_b32 s8, s92, 9
	s_mov_b64 s[0:1], 0
	s_mov_b32 s9, 0x2e8ba2e9
	s_mov_b64 s[2:3], 0x80
	s_movk_i32 s10, 0x2c00
	s_waitcnt lgkmcnt(0)
	v_mov_b64_e32 v[2:3], s[6:7]
	s_movk_i32 s6, 0x57ff
